# P2 sample-row GEMM hand-written: 32xK activations staged once in LDS, weight fragments in a rolling 24-load window (was re-reading A per column tile)
# speedup vs baseline: 1.0322x; 1.0120x over previous
; #define LAS __attribute__((address_space(3)))
; __device__ __forceinline__ int fresh_tid() { int t = threadIdx.x; asm volatile("" : "+v"(t)); return t; }
; template <class BRow>
; __device__ __forceinline__ void skinny32(LAS float* Cs, const bf16_t* A, int lda, const bf16_t* Bt, int ldb, int NC, int K, const BRow& brow) {
;     const int tid = fresh_tid(), lane = tid & 63, wave = __builtin_amdgcn_readfirstlane(tid >> 6), fr = lane & 15, fq = lane >> 4;
;     const int nct = NC >> 4, ldc = NC + 4;
;     for (int ct = wave; ct < nct; ct += NWAVES) {
;         f32x4 acc0 = {0.f, 0.f, 0.f, 0.f}, acc1 = acc0;
;         const bf16_t* ap = A + (size_t)fr * lda + fq * 8; const bf16_t* bp = Bt + (size_t)(brow(ct) + fr) * ldb + fq * 8;
;         bf16x8 a0[8], a1[8], b[8];
; #pragma unroll
;         for (int i = 0; i < 8; ++i) { a0[i] = *(const bf16x8*)(ap + 32 * i); a1[i] = *(const bf16x8*)(ap + (size_t)16 * lda + 32 * i); b[i] = *(const bf16x8*)(bp + 32 * i); }
; #pragma unroll 1
;         for (int k0 = 0; k0 < K; k0 += 256) {
;             bf16x8 n0[8], n1[8], nb[8];
;             const int kn = (k0 + 256 < K) ? k0 + 256 : k0;
; #pragma unroll
;             for (int i = 0; i < 8; ++i) { n0[i] = *(const bf16x8*)(ap + kn + 32 * i); n1[i] = *(const bf16x8*)(ap + (size_t)16 * lda + kn + 32 * i); nb[i] = *(const bf16x8*)(bp + kn + 32 * i); }
; #pragma unroll
;             for (int i = 0; i < 8; ++i) { acc0 = __builtin_amdgcn_mfma_f32_16x16x32_bf16(b[i], a0[i], acc0, 0, 0, 0); acc1 = __builtin_amdgcn_mfma_f32_16x16x32_bf16(b[i], a1[i], acc1, 0, 0, 0); }
; #pragma unroll
;             for (int i = 0; i < 8; ++i) { a0[i] = n0[i]; a1[i] = n1[i]; b[i] = nb[i]; }
;         }
;         *(LAS f32x4*)(Cs + fr * ldc + ct * 16 + 4 * fq) = acc0; *(LAS f32x4*)(Cs + (16 + fr) * ldc + ct * 16 + 4 * fq) = acc1;
; __global__ void __launch_bounds__(NTHR, 2) hymba_fwd(Params P) {
;     ...
;             skinny32(Cs, XN + (size_t)(PT + 32 * mb) * DM, DM, WIN, DM, 192, DM,
;                      [&](int ct) { const int n = 192 * ns + 16 * ct, o = n & 255; return (n & ~255) + 128 * ((o >> 5) & 1) + 32 * (o >> 6) + (o & 31); });
.LBB0_208:
	s_lshl_b32 s20, s51, 5
	s_and_b32 s52, s20, 0x1e0
	s_ashr_i32 s20, s51, 4
	s_mul_i32 s6, s20, 0xc0
	s_lshl_b32 s0, s52, 11
	s_add_u32 s0, s92, s0
	s_addc_u32 s1, s93, 0
	s_add_u32 s0, s0, 0x9800000
	s_addc_u32 s1, s1, 0
	v_mov_b32_e32 v0, v208
	v_lshrrev_b32_e32 v1, 4, v0
	v_and_b32_e32 v2, 15, v0
	v_lshlrev_b32_e32 v6, 4, v2
	v_lshl_add_u32 v6, v1, 11, v6
	global_load_dwordx4 v[32:35], v6, s[0:1]
	global_load_dwordx4 v[36:39], v6, s[0:1] offset:256
	global_load_dwordx4 v[40:43], v6, s[0:1] offset:512
	global_load_dwordx4 v[44:47], v6, s[0:1] offset:768
	global_load_dwordx4 v[48:51], v6, s[0:1] offset:1024
	global_load_dwordx4 v[60:63], v6, s[0:1] offset:1280
	global_load_dwordx4 v[64:67], v6, s[0:1] offset:1536
	global_load_dwordx4 v[68:71], v6, s[0:1] offset:1792
	v_mul_u32_u24_e32 v7, 2064, v1
	v_lshl_add_u32 v7, v2, 4, v7
	v_add_u32_e32 v7, 0x8000, v7
	v_and_b32_e32 v8, 63, v0
	v_and_b32_e32 v9, 15, v8
	v_lshrrev_b32_e32 v10, 4, v8
	v_lshlrev_b32_e32 v3, 4, v10
	v_lshl_add_u32 v3, v9, 11, v3
	v_mul_u32_u24_e32 v4, 2064, v9
	v_lshl_add_u32 v4, v10, 4, v4
	v_add_u32_e32 v4, 0x8000, v4
	v_mul_u32_u24_e32 v5, 0x310, v9
	v_lshl_add_u32 v5, v10, 4, v5
	s_lshl_b32 s20, s4, 4
	s_add_i32 s20, s20, s6
	s_and_b32 s21, s20, 0xffffff00
	s_and_b32 s29, s20, 31
	s_add_i32 s21, s21, s29
	s_bfe_u32 s29, s20, 0x10005
	s_lshl_b32 s29, s29, 7
	s_add_i32 s21, s21, s29
	s_bfe_u32 s29, s20, 0x20006
	s_lshl_b32 s29, s29, 5
	s_add_i32 s21, s21, s29
	s_lshl_b32 s21, s21, 11
	s_add_u32 s58, s92, s21
	s_addc_u32 s59, s93, 0
	s_add_u32 s58, s58, 0x200000
	s_addc_u32 s59, s59, 0
	s_add_i32 s30, s4, 8
	s_lshl_b32 s20, s30, 4
	s_add_i32 s20, s20, s6
	s_and_b32 s21, s20, 0xffffff00
	s_and_b32 s29, s20, 31
	s_add_i32 s21, s21, s29
	s_bfe_u32 s29, s20, 0x10005
	s_lshl_b32 s29, s29, 7
	s_add_i32 s21, s21, s29
	s_bfe_u32 s29, s20, 0x20006
	s_lshl_b32 s29, s29, 5
	s_add_i32 s21, s21, s29
	s_lshl_b32 s21, s21, 11
	s_add_u32 s60, s92, s21
	s_addc_u32 s61, s93, 0
	s_add_u32 s60, s60, 0x200000
	s_addc_u32 s61, s61, 0
	v_mov_b32_e32 v16, 0
	v_mov_b32_e32 v17, 0
	v_mov_b32_e32 v18, 0
	v_mov_b32_e32 v19, 0
	v_mov_b32_e32 v20, 0
	v_mov_b32_e32 v21, 0
	v_mov_b32_e32 v22, 0
	v_mov_b32_e32 v23, 0
	v_mov_b32_e32 v24, 0
	v_mov_b32_e32 v25, 0
	v_mov_b32_e32 v26, 0
	v_mov_b32_e32 v27, 0
	v_mov_b32_e32 v28, 0
	v_mov_b32_e32 v29, 0
	v_mov_b32_e32 v30, 0
	v_mov_b32_e32 v31, 0
	s_cmp_gt_i32 s4, 3
	s_cbranch_scc1 .Lmy_sk2_one
	global_load_dwordx4 v[124:127], v3, s[58:59]
	global_load_dwordx4 v[128:131], v3, s[58:59] offset:64
	global_load_dwordx4 v[132:135], v3, s[58:59] offset:128
	global_load_dwordx4 v[136:139], v3, s[58:59] offset:192
	global_load_dwordx4 v[140:143], v3, s[58:59] offset:256
	global_load_dwordx4 v[144:147], v3, s[58:59] offset:320
	global_load_dwordx4 v[148:151], v3, s[58:59] offset:384
	global_load_dwordx4 v[152:155], v3, s[58:59] offset:448
	global_load_dwordx4 v[156:159], v3, s[58:59] offset:512
	global_load_dwordx4 v[160:163], v3, s[58:59] offset:576
	global_load_dwordx4 v[164:167], v3, s[58:59] offset:640
	global_load_dwordx4 v[168:171], v3, s[58:59] offset:704
	global_load_dwordx4 v[172:175], v3, s[58:59] offset:768
	global_load_dwordx4 v[176:179], v3, s[58:59] offset:832
	global_load_dwordx4 v[180:183], v3, s[58:59] offset:896
	global_load_dwordx4 v[184:187], v3, s[58:59] offset:960
	global_load_dwordx4 v[188:191], v3, s[58:59] offset:1024
	global_load_dwordx4 v[192:195], v3, s[58:59] offset:1088
	global_load_dwordx4 v[196:199], v3, s[58:59] offset:1152
	global_load_dwordx4 v[212:215], v3, s[58:59] offset:1216
	global_load_dwordx4 v[216:219], v3, s[58:59] offset:1280
	global_load_dwordx4 v[220:223], v3, s[58:59] offset:1344
	global_load_dwordx4 v[224:227], v3, s[58:59] offset:1408
	global_load_dwordx4 v[228:231], v3, s[58:59] offset:1472
	s_waitcnt vmcnt(24)
	ds_write_b128 v7, v[32:35]
	ds_write_b128 v7, v[36:39] offset:256
	ds_write_b128 v7, v[40:43] offset:512
	ds_write_b128 v7, v[44:47] offset:768
	ds_write_b128 v7, v[48:51] offset:1024
	ds_write_b128 v7, v[60:63] offset:1280
	ds_write_b128 v7, v[64:67] offset:1536
	ds_write_b128 v7, v[68:71] offset:1792
	s_waitcnt lgkmcnt(0)
	s_barrier
	ds_read_b128 v[76:79], v4 offset:0
	ds_read_b128 v[80:83], v4 offset:33024
	ds_read_b128 v[84:87], v4 offset:64
	ds_read_b128 v[88:91], v4 offset:33088
	ds_read_b128 v[92:95], v4 offset:128
	ds_read_b128 v[96:99], v4 offset:33152
	s_waitcnt vmcnt(23) lgkmcnt(4)
	v_mfma_f32_16x16x32_bf16 v[16:19], v[124:127], v[76:79], v[16:19]
	v_mfma_f32_16x16x32_bf16 v[20:23], v[124:127], v[80:83], v[20:23]
	global_load_dwordx4 v[124:127], v3, s[58:59] offset:1536
	ds_read_b128 v[76:79], v4 offset:192
	ds_read_b128 v[80:83], v4 offset:33216
	s_waitcnt vmcnt(23) lgkmcnt(4)
	v_mfma_f32_16x16x32_bf16 v[16:19], v[128:131], v[84:87], v[16:19]
	v_mfma_f32_16x16x32_bf16 v[20:23], v[128:131], v[88:91], v[20:23]
	global_load_dwordx4 v[128:131], v3, s[58:59] offset:1600
	ds_read_b128 v[84:87], v4 offset:256
	ds_read_b128 v[88:91], v4 offset:33280
	s_waitcnt vmcnt(23) lgkmcnt(4)
	v_mfma_f32_16x16x32_bf16 v[16:19], v[132:135], v[92:95], v[16:19]
	v_mfma_f32_16x16x32_bf16 v[20:23], v[132:135], v[96:99], v[20:23]
	global_load_dwordx4 v[132:135], v3, s[58:59] offset:1664
	ds_read_b128 v[92:95], v4 offset:320
	ds_read_b128 v[96:99], v4 offset:33344
	s_waitcnt vmcnt(23) lgkmcnt(4)
	v_mfma_f32_16x16x32_bf16 v[16:19], v[136:139], v[76:79], v[16:19]
	v_mfma_f32_16x16x32_bf16 v[20:23], v[136:139], v[80:83], v[20:23]
	global_load_dwordx4 v[136:139], v3, s[58:59] offset:1728
	ds_read_b128 v[76:79], v4 offset:384
	ds_read_b128 v[80:83], v4 offset:33408
	s_waitcnt vmcnt(23) lgkmcnt(4)
; template <class BRow>
; __device__ __forceinline__ void skinny32(LAS float* Cs, const bf16_t* A, int lda, const bf16_t* Bt, int ldb, int NC, int K, const BRow& brow) {
;     ...
;         for (int k0 = 0; k0 < K; k0 += 256) {
;             bf16x8 n0[8], n1[8], nb[8];
;             const int kn = (k0 + 256 < K) ? k0 + 256 : k0;
; #pragma unroll
;             for (int i = 0; i < 8; ++i) { n0[i] = *(const bf16x8*)(ap + kn + 32 * i); n1[i] = *(const bf16x8*)(ap + (size_t)16 * lda + kn + 32 * i); nb[i] = *(const bf16x8*)(bp + kn + 32 * i); }
; #pragma unroll
;             for (int i = 0; i < 8; ++i) { acc0 = __builtin_amdgcn_mfma_f32_16x16x32_bf16(b[i], a0[i], acc0, 0, 0, 0); acc1 = __builtin_amdgcn_mfma_f32_16x16x32_bf16(b[i], a1[i], acc1, 0, 0, 0); }
	v_mfma_f32_16x16x32_bf16 v[16:19], v[140:143], v[84:87], v[16:19]
	v_mfma_f32_16x16x32_bf16 v[20:23], v[140:143], v[88:91], v[20:23]
	global_load_dwordx4 v[140:143], v3, s[58:59] offset:1792
	ds_read_b128 v[84:87], v4 offset:448
	ds_read_b128 v[88:91], v4 offset:33472
	s_waitcnt vmcnt(23) lgkmcnt(4)
	v_mfma_f32_16x16x32_bf16 v[16:19], v[144:147], v[92:95], v[16:19]
	v_mfma_f32_16x16x32_bf16 v[20:23], v[144:147], v[96:99], v[20:23]
	global_load_dwordx4 v[144:147], v3, s[58:59] offset:1856
	ds_read_b128 v[92:95], v4 offset:512
	ds_read_b128 v[96:99], v4 offset:33536
	s_waitcnt vmcnt(23) lgkmcnt(4)
	v_mfma_f32_16x16x32_bf16 v[16:19], v[148:151], v[76:79], v[16:19]
	v_mfma_f32_16x16x32_bf16 v[20:23], v[148:151], v[80:83], v[20:23]
	global_load_dwordx4 v[148:151], v3, s[58:59] offset:1920
	ds_read_b128 v[76:79], v4 offset:576
	ds_read_b128 v[80:83], v4 offset:33600
	s_waitcnt vmcnt(23) lgkmcnt(4)
	v_mfma_f32_16x16x32_bf16 v[16:19], v[152:155], v[84:87], v[16:19]
	v_mfma_f32_16x16x32_bf16 v[20:23], v[152:155], v[88:91], v[20:23]
	global_load_dwordx4 v[152:155], v3, s[58:59] offset:1984
	ds_read_b128 v[84:87], v4 offset:640
	ds_read_b128 v[88:91], v4 offset:33664
	s_waitcnt vmcnt(23) lgkmcnt(4)
	v_mfma_f32_16x16x32_bf16 v[16:19], v[156:159], v[92:95], v[16:19]
	v_mfma_f32_16x16x32_bf16 v[20:23], v[156:159], v[96:99], v[20:23]
	global_load_dwordx4 v[156:159], v3, s[60:61]
	ds_read_b128 v[92:95], v4 offset:704
	ds_read_b128 v[96:99], v4 offset:33728
	s_waitcnt vmcnt(23) lgkmcnt(4)
	v_mfma_f32_16x16x32_bf16 v[16:19], v[160:163], v[76:79], v[16:19]
	v_mfma_f32_16x16x32_bf16 v[20:23], v[160:163], v[80:83], v[20:23]
	global_load_dwordx4 v[160:163], v3, s[60:61] offset:64
	ds_read_b128 v[76:79], v4 offset:768
	ds_read_b128 v[80:83], v4 offset:33792
	s_waitcnt vmcnt(23) lgkmcnt(4)
	v_mfma_f32_16x16x32_bf16 v[16:19], v[164:167], v[84:87], v[16:19]
	v_mfma_f32_16x16x32_bf16 v[20:23], v[164:167], v[88:91], v[20:23]
	global_load_dwordx4 v[164:167], v3, s[60:61] offset:128
	ds_read_b128 v[84:87], v4 offset:832
	ds_read_b128 v[88:91], v4 offset:33856
	s_waitcnt vmcnt(23) lgkmcnt(4)
	v_mfma_f32_16x16x32_bf16 v[16:19], v[168:171], v[92:95], v[16:19]
	v_mfma_f32_16x16x32_bf16 v[20:23], v[168:171], v[96:99], v[20:23]
	global_load_dwordx4 v[168:171], v3, s[60:61] offset:192
	ds_read_b128 v[92:95], v4 offset:896
	ds_read_b128 v[96:99], v4 offset:33920
	s_waitcnt vmcnt(23) lgkmcnt(4)
	v_mfma_f32_16x16x32_bf16 v[16:19], v[172:175], v[76:79], v[16:19]
	v_mfma_f32_16x16x32_bf16 v[20:23], v[172:175], v[80:83], v[20:23]
	global_load_dwordx4 v[172:175], v3, s[60:61] offset:256
	ds_read_b128 v[76:79], v4 offset:960
	ds_read_b128 v[80:83], v4 offset:33984
	s_waitcnt vmcnt(23) lgkmcnt(4)
	v_mfma_f32_16x16x32_bf16 v[16:19], v[176:179], v[84:87], v[16:19]
	v_mfma_f32_16x16x32_bf16 v[20:23], v[176:179], v[88:91], v[20:23]
	global_load_dwordx4 v[176:179], v3, s[60:61] offset:320
	ds_read_b128 v[84:87], v4 offset:1024
	ds_read_b128 v[88:91], v4 offset:34048
	s_waitcnt vmcnt(23) lgkmcnt(4)
	v_mfma_f32_16x16x32_bf16 v[16:19], v[180:183], v[92:95], v[16:19]
	v_mfma_f32_16x16x32_bf16 v[20:23], v[180:183], v[96:99], v[20:23]
	global_load_dwordx4 v[180:183], v3, s[60:61] offset:384
	ds_read_b128 v[92:95], v4 offset:1088
	ds_read_b128 v[96:99], v4 offset:34112
	s_waitcnt vmcnt(23) lgkmcnt(4)
	v_mfma_f32_16x16x32_bf16 v[16:19], v[184:187], v[76:79], v[16:19]
	v_mfma_f32_16x16x32_bf16 v[20:23], v[184:187], v[80:83], v[20:23]
	global_load_dwordx4 v[184:187], v3, s[60:61] offset:448
	ds_read_b128 v[76:79], v4 offset:1152
	ds_read_b128 v[80:83], v4 offset:34176
	s_waitcnt vmcnt(23) lgkmcnt(4)
	v_mfma_f32_16x16x32_bf16 v[16:19], v[188:191], v[84:87], v[16:19]
	v_mfma_f32_16x16x32_bf16 v[20:23], v[188:191], v[88:91], v[20:23]
	global_load_dwordx4 v[188:191], v3, s[60:61] offset:512
	ds_read_b128 v[84:87], v4 offset:1216
	ds_read_b128 v[88:91], v4 offset:34240
	s_waitcnt vmcnt(23) lgkmcnt(4)
	v_mfma_f32_16x16x32_bf16 v[16:19], v[192:195], v[92:95], v[16:19]
	v_mfma_f32_16x16x32_bf16 v[20:23], v[192:195], v[96:99], v[20:23]
	global_load_dwordx4 v[192:195], v3, s[60:61] offset:576
	ds_read_b128 v[92:95], v4 offset:1280
	ds_read_b128 v[96:99], v4 offset:34304
	s_waitcnt vmcnt(23) lgkmcnt(4)
	v_mfma_f32_16x16x32_bf16 v[16:19], v[196:199], v[76:79], v[16:19]
	v_mfma_f32_16x16x32_bf16 v[20:23], v[196:199], v[80:83], v[20:23]
	global_load_dwordx4 v[196:199], v3, s[60:61] offset:640
	ds_read_b128 v[76:79], v4 offset:1344
	ds_read_b128 v[80:83], v4 offset:34368
	s_waitcnt vmcnt(23) lgkmcnt(4)
	v_mfma_f32_16x16x32_bf16 v[16:19], v[212:215], v[84:87], v[16:19]
	v_mfma_f32_16x16x32_bf16 v[20:23], v[212:215], v[88:91], v[20:23]
	global_load_dwordx4 v[212:215], v3, s[60:61] offset:704
	ds_read_b128 v[84:87], v4 offset:1408
	ds_read_b128 v[88:91], v4 offset:34432
	s_waitcnt vmcnt(23) lgkmcnt(4)
	v_mfma_f32_16x16x32_bf16 v[16:19], v[216:219], v[92:95], v[16:19]
	v_mfma_f32_16x16x32_bf16 v[20:23], v[216:219], v[96:99], v[20:23]
	global_load_dwordx4 v[216:219], v3, s[60:61] offset:768
	ds_read_b128 v[92:95], v4 offset:1472
	ds_read_b128 v[96:99], v4 offset:34496
	s_waitcnt vmcnt(23) lgkmcnt(4)
	v_mfma_f32_16x16x32_bf16 v[16:19], v[220:223], v[76:79], v[16:19]
	v_mfma_f32_16x16x32_bf16 v[20:23], v[220:223], v[80:83], v[20:23]
	global_load_dwordx4 v[220:223], v3, s[60:61] offset:832
	ds_read_b128 v[76:79], v4 offset:1536
	ds_read_b128 v[80:83], v4 offset:34560
	s_waitcnt vmcnt(23) lgkmcnt(4)
	v_mfma_f32_16x16x32_bf16 v[16:19], v[224:227], v[84:87], v[16:19]
	v_mfma_f32_16x16x32_bf16 v[20:23], v[224:227], v[88:91], v[20:23]
	global_load_dwordx4 v[224:227], v3, s[60:61] offset:896
	ds_read_b128 v[84:87], v4 offset:1600
	ds_read_b128 v[88:91], v4 offset:34624
	s_waitcnt vmcnt(23) lgkmcnt(4)
; template <class BRow>
; __device__ __forceinline__ void skinny32(LAS float* Cs, const bf16_t* A, int lda, const bf16_t* Bt, int ldb, int NC, int K, const BRow& brow) {
;     ...
;         for (int k0 = 0; k0 < K; k0 += 256) {
;             bf16x8 n0[8], n1[8], nb[8];
;             const int kn = (k0 + 256 < K) ? k0 + 256 : k0;
; #pragma unroll
;             for (int i = 0; i < 8; ++i) { n0[i] = *(const bf16x8*)(ap + kn + 32 * i); n1[i] = *(const bf16x8*)(ap + (size_t)16 * lda + kn + 32 * i); nb[i] = *(const bf16x8*)(bp + kn + 32 * i); }
; #pragma unroll
;             for (int i = 0; i < 8; ++i) { acc0 = __builtin_amdgcn_mfma_f32_16x16x32_bf16(b[i], a0[i], acc0, 0, 0, 0); acc1 = __builtin_amdgcn_mfma_f32_16x16x32_bf16(b[i], a1[i], acc1, 0, 0, 0); }
	v_mfma_f32_16x16x32_bf16 v[16:19], v[228:231], v[92:95], v[16:19]
	v_mfma_f32_16x16x32_bf16 v[20:23], v[228:231], v[96:99], v[20:23]
	global_load_dwordx4 v[228:231], v3, s[60:61] offset:960
	ds_read_b128 v[92:95], v4 offset:1664
	ds_read_b128 v[96:99], v4 offset:34688
	s_waitcnt vmcnt(23) lgkmcnt(4)
	v_mfma_f32_16x16x32_bf16 v[16:19], v[124:127], v[76:79], v[16:19]
	v_mfma_f32_16x16x32_bf16 v[20:23], v[124:127], v[80:83], v[20:23]
	global_load_dwordx4 v[124:127], v3, s[60:61] offset:1024
	ds_read_b128 v[76:79], v4 offset:1728
	ds_read_b128 v[80:83], v4 offset:34752
	s_waitcnt vmcnt(23) lgkmcnt(4)
	v_mfma_f32_16x16x32_bf16 v[16:19], v[128:131], v[84:87], v[16:19]
	v_mfma_f32_16x16x32_bf16 v[20:23], v[128:131], v[88:91], v[20:23]
	global_load_dwordx4 v[128:131], v3, s[60:61] offset:1088
	ds_read_b128 v[84:87], v4 offset:1792
	ds_read_b128 v[88:91], v4 offset:34816
	s_waitcnt vmcnt(23) lgkmcnt(4)
	v_mfma_f32_16x16x32_bf16 v[16:19], v[132:135], v[92:95], v[16:19]
	v_mfma_f32_16x16x32_bf16 v[20:23], v[132:135], v[96:99], v[20:23]
	global_load_dwordx4 v[132:135], v3, s[60:61] offset:1152
	ds_read_b128 v[92:95], v4 offset:1856
	ds_read_b128 v[96:99], v4 offset:34880
	s_waitcnt vmcnt(23) lgkmcnt(4)
	v_mfma_f32_16x16x32_bf16 v[16:19], v[136:139], v[76:79], v[16:19]
	v_mfma_f32_16x16x32_bf16 v[20:23], v[136:139], v[80:83], v[20:23]
	global_load_dwordx4 v[136:139], v3, s[60:61] offset:1216
	ds_read_b128 v[76:79], v4 offset:1920
	ds_read_b128 v[80:83], v4 offset:34944
	s_waitcnt vmcnt(23) lgkmcnt(4)
	v_mfma_f32_16x16x32_bf16 v[16:19], v[140:143], v[84:87], v[16:19]
	v_mfma_f32_16x16x32_bf16 v[20:23], v[140:143], v[88:91], v[20:23]
	global_load_dwordx4 v[140:143], v3, s[60:61] offset:1280
	ds_read_b128 v[84:87], v4 offset:1984
	ds_read_b128 v[88:91], v4 offset:35008
	s_waitcnt vmcnt(23) lgkmcnt(4)
	v_mfma_f32_16x16x32_bf16 v[16:19], v[144:147], v[92:95], v[16:19]
	v_mfma_f32_16x16x32_bf16 v[20:23], v[144:147], v[96:99], v[20:23]
	global_load_dwordx4 v[144:147], v3, s[60:61] offset:1344
	ds_read_b128 v[92:95], v4 offset:0
	ds_read_b128 v[96:99], v4 offset:33024
	s_waitcnt vmcnt(23) lgkmcnt(4)
	v_mfma_f32_16x16x32_bf16 v[16:19], v[148:151], v[76:79], v[16:19]
	v_mfma_f32_16x16x32_bf16 v[20:23], v[148:151], v[80:83], v[20:23]
	global_load_dwordx4 v[148:151], v3, s[60:61] offset:1408
	ds_read_b128 v[76:79], v4 offset:64
	ds_read_b128 v[80:83], v4 offset:33088
	s_waitcnt vmcnt(23) lgkmcnt(4)
	v_mfma_f32_16x16x32_bf16 v[16:19], v[152:155], v[84:87], v[16:19]
	v_mfma_f32_16x16x32_bf16 v[20:23], v[152:155], v[88:91], v[20:23]
	global_load_dwordx4 v[152:155], v3, s[60:61] offset:1472
	ds_read_b128 v[84:87], v4 offset:128
	ds_read_b128 v[88:91], v4 offset:33152
	s_waitcnt vmcnt(23) lgkmcnt(4)
	v_mfma_f32_16x16x32_bf16 v[24:27], v[156:159], v[92:95], v[24:27]
	v_mfma_f32_16x16x32_bf16 v[28:31], v[156:159], v[96:99], v[28:31]
	global_load_dwordx4 v[156:159], v3, s[60:61] offset:1536
	ds_read_b128 v[92:95], v4 offset:192
	ds_read_b128 v[96:99], v4 offset:33216
	s_waitcnt vmcnt(23) lgkmcnt(4)
	v_mfma_f32_16x16x32_bf16 v[24:27], v[160:163], v[76:79], v[24:27]
	v_mfma_f32_16x16x32_bf16 v[28:31], v[160:163], v[80:83], v[28:31]
	global_load_dwordx4 v[160:163], v3, s[60:61] offset:1600
	ds_read_b128 v[76:79], v4 offset:256
	ds_read_b128 v[80:83], v4 offset:33280
	s_waitcnt vmcnt(23) lgkmcnt(4)
	v_mfma_f32_16x16x32_bf16 v[24:27], v[164:167], v[84:87], v[24:27]
	v_mfma_f32_16x16x32_bf16 v[28:31], v[164:167], v[88:91], v[28:31]
	global_load_dwordx4 v[164:167], v3, s[60:61] offset:1664
	ds_read_b128 v[84:87], v4 offset:320
	ds_read_b128 v[88:91], v4 offset:33344
	s_waitcnt vmcnt(23) lgkmcnt(4)
	v_mfma_f32_16x16x32_bf16 v[24:27], v[168:171], v[92:95], v[24:27]
	v_mfma_f32_16x16x32_bf16 v[28:31], v[168:171], v[96:99], v[28:31]
	global_load_dwordx4 v[168:171], v3, s[60:61] offset:1728
	ds_read_b128 v[92:95], v4 offset:384
	ds_read_b128 v[96:99], v4 offset:33408
	s_waitcnt vmcnt(23) lgkmcnt(4)
	v_mfma_f32_16x16x32_bf16 v[24:27], v[172:175], v[76:79], v[24:27]
	v_mfma_f32_16x16x32_bf16 v[28:31], v[172:175], v[80:83], v[28:31]
	global_load_dwordx4 v[172:175], v3, s[60:61] offset:1792
	ds_read_b128 v[76:79], v4 offset:448
	ds_read_b128 v[80:83], v4 offset:33472
	s_waitcnt vmcnt(23) lgkmcnt(4)
	v_mfma_f32_16x16x32_bf16 v[24:27], v[176:179], v[84:87], v[24:27]
	v_mfma_f32_16x16x32_bf16 v[28:31], v[176:179], v[88:91], v[28:31]
	global_load_dwordx4 v[176:179], v3, s[60:61] offset:1856
	ds_read_b128 v[84:87], v4 offset:512
	ds_read_b128 v[88:91], v4 offset:33536
	s_waitcnt vmcnt(23) lgkmcnt(4)
	v_mfma_f32_16x16x32_bf16 v[24:27], v[180:183], v[92:95], v[24:27]
	v_mfma_f32_16x16x32_bf16 v[28:31], v[180:183], v[96:99], v[28:31]
	global_load_dwordx4 v[180:183], v3, s[60:61] offset:1920
	ds_read_b128 v[92:95], v4 offset:576
	ds_read_b128 v[96:99], v4 offset:33600
	s_waitcnt vmcnt(23) lgkmcnt(4)
	v_mfma_f32_16x16x32_bf16 v[24:27], v[184:187], v[76:79], v[24:27]
	v_mfma_f32_16x16x32_bf16 v[28:31], v[184:187], v[80:83], v[28:31]
	global_load_dwordx4 v[184:187], v3, s[60:61] offset:1984
	ds_read_b128 v[76:79], v4 offset:640
	ds_read_b128 v[80:83], v4 offset:33664
	s_waitcnt vmcnt(23) lgkmcnt(4)
	v_mfma_f32_16x16x32_bf16 v[24:27], v[188:191], v[84:87], v[24:27]
	v_mfma_f32_16x16x32_bf16 v[28:31], v[188:191], v[88:91], v[28:31]
	ds_read_b128 v[84:87], v4 offset:704
	ds_read_b128 v[88:91], v4 offset:33728
	s_waitcnt vmcnt(22) lgkmcnt(4)
	v_mfma_f32_16x16x32_bf16 v[24:27], v[192:195], v[92:95], v[24:27]
	v_mfma_f32_16x16x32_bf16 v[28:31], v[192:195], v[96:99], v[28:31]
	ds_read_b128 v[92:95], v4 offset:768
	ds_read_b128 v[96:99], v4 offset:33792
	s_waitcnt vmcnt(21) lgkmcnt(4)
; #define LAS __attribute__((address_space(3)))
; template <class BRow>
; __device__ __forceinline__ void skinny32(LAS float* Cs, const bf16_t* A, int lda, const bf16_t* Bt, int ldb, int NC, int K, const BRow& brow) {
;     ...
;         for (int k0 = 0; k0 < K; k0 += 256) {
;             bf16x8 n0[8], n1[8], nb[8];
;             const int kn = (k0 + 256 < K) ? k0 + 256 : k0;
; #pragma unroll
;             for (int i = 0; i < 8; ++i) { n0[i] = *(const bf16x8*)(ap + kn + 32 * i); n1[i] = *(const bf16x8*)(ap + (size_t)16 * lda + kn + 32 * i); nb[i] = *(const bf16x8*)(bp + kn + 32 * i); }
; #pragma unroll
;             for (int i = 0; i < 8; ++i) { acc0 = __builtin_amdgcn_mfma_f32_16x16x32_bf16(b[i], a0[i], acc0, 0, 0, 0); acc1 = __builtin_amdgcn_mfma_f32_16x16x32_bf16(b[i], a1[i], acc1, 0, 0, 0); }
; #pragma unroll
;             for (int i = 0; i < 8; ++i) { a0[i] = n0[i]; a1[i] = n1[i]; b[i] = nb[i]; }
;         }
;         *(LAS f32x4*)(Cs + fr * ldc + ct * 16 + 4 * fq) = acc0; *(LAS f32x4*)(Cs + (16 + fr) * ldc + ct * 16 + 4 * fq) = acc1;
	v_mfma_f32_16x16x32_bf16 v[24:27], v[196:199], v[76:79], v[24:27]
	v_mfma_f32_16x16x32_bf16 v[28:31], v[196:199], v[80:83], v[28:31]
	ds_read_b128 v[76:79], v4 offset:832
	ds_read_b128 v[80:83], v4 offset:33856
	s_waitcnt vmcnt(20) lgkmcnt(4)
	v_mfma_f32_16x16x32_bf16 v[24:27], v[212:215], v[84:87], v[24:27]
	v_mfma_f32_16x16x32_bf16 v[28:31], v[212:215], v[88:91], v[28:31]
	ds_read_b128 v[84:87], v4 offset:896
	ds_read_b128 v[88:91], v4 offset:33920
	s_waitcnt vmcnt(19) lgkmcnt(4)
	v_mfma_f32_16x16x32_bf16 v[24:27], v[216:219], v[92:95], v[24:27]
	v_mfma_f32_16x16x32_bf16 v[28:31], v[216:219], v[96:99], v[28:31]
	ds_read_b128 v[92:95], v4 offset:960
	ds_read_b128 v[96:99], v4 offset:33984
	s_waitcnt vmcnt(18) lgkmcnt(4)
	v_mfma_f32_16x16x32_bf16 v[24:27], v[220:223], v[76:79], v[24:27]
	v_mfma_f32_16x16x32_bf16 v[28:31], v[220:223], v[80:83], v[28:31]
	ds_read_b128 v[76:79], v4 offset:1024
	ds_read_b128 v[80:83], v4 offset:34048
	s_waitcnt vmcnt(17) lgkmcnt(4)
	v_mfma_f32_16x16x32_bf16 v[24:27], v[224:227], v[84:87], v[24:27]
	v_mfma_f32_16x16x32_bf16 v[28:31], v[224:227], v[88:91], v[28:31]
	ds_read_b128 v[84:87], v4 offset:1088
	ds_read_b128 v[88:91], v4 offset:34112
	s_waitcnt vmcnt(16) lgkmcnt(4)
	v_mfma_f32_16x16x32_bf16 v[24:27], v[228:231], v[92:95], v[24:27]
	v_mfma_f32_16x16x32_bf16 v[28:31], v[228:231], v[96:99], v[28:31]
	ds_read_b128 v[92:95], v4 offset:1152
	ds_read_b128 v[96:99], v4 offset:34176
	s_waitcnt vmcnt(15) lgkmcnt(4)
	v_mfma_f32_16x16x32_bf16 v[24:27], v[124:127], v[76:79], v[24:27]
	v_mfma_f32_16x16x32_bf16 v[28:31], v[124:127], v[80:83], v[28:31]
	ds_read_b128 v[76:79], v4 offset:1216
	ds_read_b128 v[80:83], v4 offset:34240
	s_waitcnt vmcnt(14) lgkmcnt(4)
	v_mfma_f32_16x16x32_bf16 v[24:27], v[128:131], v[84:87], v[24:27]
	v_mfma_f32_16x16x32_bf16 v[28:31], v[128:131], v[88:91], v[28:31]
	ds_read_b128 v[84:87], v4 offset:1280
	ds_read_b128 v[88:91], v4 offset:34304
	s_waitcnt vmcnt(13) lgkmcnt(4)
	v_mfma_f32_16x16x32_bf16 v[24:27], v[132:135], v[92:95], v[24:27]
	v_mfma_f32_16x16x32_bf16 v[28:31], v[132:135], v[96:99], v[28:31]
	ds_read_b128 v[92:95], v4 offset:1344
	ds_read_b128 v[96:99], v4 offset:34368
	s_waitcnt vmcnt(12) lgkmcnt(4)
	v_mfma_f32_16x16x32_bf16 v[24:27], v[136:139], v[76:79], v[24:27]
	v_mfma_f32_16x16x32_bf16 v[28:31], v[136:139], v[80:83], v[28:31]
	ds_read_b128 v[76:79], v4 offset:1408
	ds_read_b128 v[80:83], v4 offset:34432
	s_waitcnt vmcnt(11) lgkmcnt(4)
	v_mfma_f32_16x16x32_bf16 v[24:27], v[140:143], v[84:87], v[24:27]
	v_mfma_f32_16x16x32_bf16 v[28:31], v[140:143], v[88:91], v[28:31]
	ds_read_b128 v[84:87], v4 offset:1472
	ds_read_b128 v[88:91], v4 offset:34496
	s_waitcnt vmcnt(10) lgkmcnt(4)
	v_mfma_f32_16x16x32_bf16 v[24:27], v[144:147], v[92:95], v[24:27]
	v_mfma_f32_16x16x32_bf16 v[28:31], v[144:147], v[96:99], v[28:31]
	ds_read_b128 v[92:95], v4 offset:1536
	ds_read_b128 v[96:99], v4 offset:34560
	s_waitcnt vmcnt(9) lgkmcnt(4)
	v_mfma_f32_16x16x32_bf16 v[24:27], v[148:151], v[76:79], v[24:27]
	v_mfma_f32_16x16x32_bf16 v[28:31], v[148:151], v[80:83], v[28:31]
	ds_read_b128 v[76:79], v4 offset:1600
	ds_read_b128 v[80:83], v4 offset:34624
	s_waitcnt vmcnt(8) lgkmcnt(4)
	v_mfma_f32_16x16x32_bf16 v[24:27], v[152:155], v[84:87], v[24:27]
	v_mfma_f32_16x16x32_bf16 v[28:31], v[152:155], v[88:91], v[28:31]
	ds_read_b128 v[84:87], v4 offset:1664
	ds_read_b128 v[88:91], v4 offset:34688
	s_waitcnt vmcnt(7) lgkmcnt(4)
	v_mfma_f32_16x16x32_bf16 v[24:27], v[156:159], v[92:95], v[24:27]
	v_mfma_f32_16x16x32_bf16 v[28:31], v[156:159], v[96:99], v[28:31]
	ds_read_b128 v[92:95], v4 offset:1728
	ds_read_b128 v[96:99], v4 offset:34752
	s_waitcnt vmcnt(6) lgkmcnt(4)
	v_mfma_f32_16x16x32_bf16 v[24:27], v[160:163], v[76:79], v[24:27]
	v_mfma_f32_16x16x32_bf16 v[28:31], v[160:163], v[80:83], v[28:31]
	ds_read_b128 v[76:79], v4 offset:1792
	ds_read_b128 v[80:83], v4 offset:34816
	s_waitcnt vmcnt(5) lgkmcnt(4)
	v_mfma_f32_16x16x32_bf16 v[24:27], v[164:167], v[84:87], v[24:27]
	v_mfma_f32_16x16x32_bf16 v[28:31], v[164:167], v[88:91], v[28:31]
	ds_read_b128 v[84:87], v4 offset:1856
	ds_read_b128 v[88:91], v4 offset:34880
	s_waitcnt vmcnt(4) lgkmcnt(4)
	v_mfma_f32_16x16x32_bf16 v[24:27], v[168:171], v[92:95], v[24:27]
	v_mfma_f32_16x16x32_bf16 v[28:31], v[168:171], v[96:99], v[28:31]
	ds_read_b128 v[92:95], v4 offset:1920
	ds_read_b128 v[96:99], v4 offset:34944
	s_waitcnt vmcnt(3) lgkmcnt(4)
	v_mfma_f32_16x16x32_bf16 v[24:27], v[172:175], v[76:79], v[24:27]
	v_mfma_f32_16x16x32_bf16 v[28:31], v[172:175], v[80:83], v[28:31]
	ds_read_b128 v[76:79], v4 offset:1984
	ds_read_b128 v[80:83], v4 offset:35008
	s_waitcnt vmcnt(2) lgkmcnt(4)
	v_mfma_f32_16x16x32_bf16 v[24:27], v[176:179], v[84:87], v[24:27]
	v_mfma_f32_16x16x32_bf16 v[28:31], v[176:179], v[88:91], v[28:31]
	s_waitcnt vmcnt(1) lgkmcnt(2)
	v_mfma_f32_16x16x32_bf16 v[24:27], v[180:183], v[92:95], v[24:27]
	v_mfma_f32_16x16x32_bf16 v[28:31], v[180:183], v[96:99], v[28:31]
	s_waitcnt vmcnt(0) lgkmcnt(0)
	v_mfma_f32_16x16x32_bf16 v[24:27], v[184:187], v[76:79], v[24:27]
	v_mfma_f32_16x16x32_bf16 v[28:31], v[184:187], v[80:83], v[28:31]
	s_nop 7
	s_nop 3
	s_lshl_b32 s20, s4, 6
	v_add_u32_e32 v6, s20, v5
	ds_write_b128 v6, v[16:19]
	ds_write_b128 v6, v[20:23] offset:12544
	s_lshl_b32 s20, s30, 6
	v_add_u32_e32 v6, s20, v5
	ds_write_b128 v6, v[24:27]
	ds_write_b128 v6, v[28:31] offset:12544
	s_branch .Lmy_sk2_done
; template <class BRow>
; __device__ __forceinline__ void skinny32(LAS float* Cs, const bf16_t* A, int lda, const bf16_t* Bt, int ldb, int NC, int K, const BRow& brow) {
;     ...
;         const bf16_t* ap = A + (size_t)fr * lda + fq * 8; const bf16_t* bp = Bt + (size_t)(brow(ct) + fr) * ldb + fq * 8;
;         bf16x8 a0[8], a1[8], b[8];
; #pragma unroll
;         for (int i = 0; i < 8; ++i) { a0[i] = *(const bf16x8*)(ap + 32 * i); a1[i] = *(const bf16x8*)(ap + (size_t)16 * lda + 32 * i); b[i] = *(const bf16x8*)(bp + 32 * i); }
; #pragma unroll 1
;         for (int k0 = 0; k0 < K; k0 += 256) {
;             bf16x8 n0[8], n1[8], nb[8];
;             const int kn = (k0 + 256 < K) ? k0 + 256 : k0;
; #pragma unroll
;             for (int i = 0; i < 8; ++i) { n0[i] = *(const bf16x8*)(ap + kn + 32 * i); n1[i] = *(const bf16x8*)(ap + (size_t)16 * lda + kn + 32 * i); nb[i] = *(const bf16x8*)(bp + kn + 32 * i); }
; #pragma unroll
;             for (int i = 0; i < 8; ++i) { acc0 = __builtin_amdgcn_mfma_f32_16x16x32_bf16(b[i], a0[i], acc0, 0, 0, 0); acc1 = __builtin_amdgcn_mfma_f32_16x16x32_bf16(b[i], a1[i], acc1, 0, 0, 0); }
.Lmy_sk2_one:
	global_load_dwordx4 v[124:127], v3, s[58:59]
	global_load_dwordx4 v[128:131], v3, s[58:59] offset:64
	global_load_dwordx4 v[132:135], v3, s[58:59] offset:128
	global_load_dwordx4 v[136:139], v3, s[58:59] offset:192
	global_load_dwordx4 v[140:143], v3, s[58:59] offset:256
	global_load_dwordx4 v[144:147], v3, s[58:59] offset:320
	global_load_dwordx4 v[148:151], v3, s[58:59] offset:384
	global_load_dwordx4 v[152:155], v3, s[58:59] offset:448
	global_load_dwordx4 v[156:159], v3, s[58:59] offset:512
	global_load_dwordx4 v[160:163], v3, s[58:59] offset:576
	global_load_dwordx4 v[164:167], v3, s[58:59] offset:640
	global_load_dwordx4 v[168:171], v3, s[58:59] offset:704
	global_load_dwordx4 v[172:175], v3, s[58:59] offset:768
	global_load_dwordx4 v[176:179], v3, s[58:59] offset:832
	global_load_dwordx4 v[180:183], v3, s[58:59] offset:896
	global_load_dwordx4 v[184:187], v3, s[58:59] offset:960
	global_load_dwordx4 v[188:191], v3, s[58:59] offset:1024
	global_load_dwordx4 v[192:195], v3, s[58:59] offset:1088
	global_load_dwordx4 v[196:199], v3, s[58:59] offset:1152
	global_load_dwordx4 v[212:215], v3, s[58:59] offset:1216
	global_load_dwordx4 v[216:219], v3, s[58:59] offset:1280
	global_load_dwordx4 v[220:223], v3, s[58:59] offset:1344
	global_load_dwordx4 v[224:227], v3, s[58:59] offset:1408
	global_load_dwordx4 v[228:231], v3, s[58:59] offset:1472
	s_waitcnt vmcnt(24)
	ds_write_b128 v7, v[32:35]
	ds_write_b128 v7, v[36:39] offset:256
	ds_write_b128 v7, v[40:43] offset:512
	ds_write_b128 v7, v[44:47] offset:768
	ds_write_b128 v7, v[48:51] offset:1024
	ds_write_b128 v7, v[60:63] offset:1280
	ds_write_b128 v7, v[64:67] offset:1536
	ds_write_b128 v7, v[68:71] offset:1792
	s_waitcnt lgkmcnt(0)
	s_barrier
	ds_read_b128 v[76:79], v4 offset:0
	ds_read_b128 v[80:83], v4 offset:33024
	ds_read_b128 v[84:87], v4 offset:64
	ds_read_b128 v[88:91], v4 offset:33088
	ds_read_b128 v[92:95], v4 offset:128
	ds_read_b128 v[96:99], v4 offset:33152
	s_waitcnt vmcnt(23) lgkmcnt(4)
	v_mfma_f32_16x16x32_bf16 v[16:19], v[124:127], v[76:79], v[16:19]
	v_mfma_f32_16x16x32_bf16 v[20:23], v[124:127], v[80:83], v[20:23]
	global_load_dwordx4 v[124:127], v3, s[58:59] offset:1536
	ds_read_b128 v[76:79], v4 offset:192
	ds_read_b128 v[80:83], v4 offset:33216
	s_waitcnt vmcnt(23) lgkmcnt(4)
	v_mfma_f32_16x16x32_bf16 v[16:19], v[128:131], v[84:87], v[16:19]
	v_mfma_f32_16x16x32_bf16 v[20:23], v[128:131], v[88:91], v[20:23]
	global_load_dwordx4 v[128:131], v3, s[58:59] offset:1600
	ds_read_b128 v[84:87], v4 offset:256
	ds_read_b128 v[88:91], v4 offset:33280
	s_waitcnt vmcnt(23) lgkmcnt(4)
	v_mfma_f32_16x16x32_bf16 v[16:19], v[132:135], v[92:95], v[16:19]
	v_mfma_f32_16x16x32_bf16 v[20:23], v[132:135], v[96:99], v[20:23]
	global_load_dwordx4 v[132:135], v3, s[58:59] offset:1664
	ds_read_b128 v[92:95], v4 offset:320
	ds_read_b128 v[96:99], v4 offset:33344
	s_waitcnt vmcnt(23) lgkmcnt(4)
	v_mfma_f32_16x16x32_bf16 v[16:19], v[136:139], v[76:79], v[16:19]
	v_mfma_f32_16x16x32_bf16 v[20:23], v[136:139], v[80:83], v[20:23]
	global_load_dwordx4 v[136:139], v3, s[58:59] offset:1728
	ds_read_b128 v[76:79], v4 offset:384
	ds_read_b128 v[80:83], v4 offset:33408
	s_waitcnt vmcnt(23) lgkmcnt(4)
	v_mfma_f32_16x16x32_bf16 v[16:19], v[140:143], v[84:87], v[16:19]
	v_mfma_f32_16x16x32_bf16 v[20:23], v[140:143], v[88:91], v[20:23]
	global_load_dwordx4 v[140:143], v3, s[58:59] offset:1792
	ds_read_b128 v[84:87], v4 offset:448
	ds_read_b128 v[88:91], v4 offset:33472
	s_waitcnt vmcnt(23) lgkmcnt(4)
	v_mfma_f32_16x16x32_bf16 v[16:19], v[144:147], v[92:95], v[16:19]
	v_mfma_f32_16x16x32_bf16 v[20:23], v[144:147], v[96:99], v[20:23]
	global_load_dwordx4 v[144:147], v3, s[58:59] offset:1856
	ds_read_b128 v[92:95], v4 offset:512
	ds_read_b128 v[96:99], v4 offset:33536
	s_waitcnt vmcnt(23) lgkmcnt(4)
	v_mfma_f32_16x16x32_bf16 v[16:19], v[148:151], v[76:79], v[16:19]
	v_mfma_f32_16x16x32_bf16 v[20:23], v[148:151], v[80:83], v[20:23]
	global_load_dwordx4 v[148:151], v3, s[58:59] offset:1920
	ds_read_b128 v[76:79], v4 offset:576
	ds_read_b128 v[80:83], v4 offset:33600
	s_waitcnt vmcnt(23) lgkmcnt(4)
	v_mfma_f32_16x16x32_bf16 v[16:19], v[152:155], v[84:87], v[16:19]
	v_mfma_f32_16x16x32_bf16 v[20:23], v[152:155], v[88:91], v[20:23]
	global_load_dwordx4 v[152:155], v3, s[58:59] offset:1984
	ds_read_b128 v[84:87], v4 offset:640
	ds_read_b128 v[88:91], v4 offset:33664
	s_waitcnt vmcnt(23) lgkmcnt(4)
	v_mfma_f32_16x16x32_bf16 v[16:19], v[156:159], v[92:95], v[16:19]
	v_mfma_f32_16x16x32_bf16 v[20:23], v[156:159], v[96:99], v[20:23]
	ds_read_b128 v[92:95], v4 offset:704
	ds_read_b128 v[96:99], v4 offset:33728
	s_waitcnt vmcnt(22) lgkmcnt(4)
	v_mfma_f32_16x16x32_bf16 v[16:19], v[160:163], v[76:79], v[16:19]
	v_mfma_f32_16x16x32_bf16 v[20:23], v[160:163], v[80:83], v[20:23]
	ds_read_b128 v[76:79], v4 offset:768
	ds_read_b128 v[80:83], v4 offset:33792
	s_waitcnt vmcnt(21) lgkmcnt(4)
	v_mfma_f32_16x16x32_bf16 v[16:19], v[164:167], v[84:87], v[16:19]
	v_mfma_f32_16x16x32_bf16 v[20:23], v[164:167], v[88:91], v[20:23]
	ds_read_b128 v[84:87], v4 offset:832
	ds_read_b128 v[88:91], v4 offset:33856
	s_waitcnt vmcnt(20) lgkmcnt(4)
; #define LAS __attribute__((address_space(3)))
; template <class BRow>
; __device__ __forceinline__ void skinny32(LAS float* Cs, const bf16_t* A, int lda, const bf16_t* Bt, int ldb, int NC, int K, const BRow& brow) {
;     ...
;         for (int k0 = 0; k0 < K; k0 += 256) {
;             bf16x8 n0[8], n1[8], nb[8];
;             const int kn = (k0 + 256 < K) ? k0 + 256 : k0;
; #pragma unroll
;             for (int i = 0; i < 8; ++i) { n0[i] = *(const bf16x8*)(ap + kn + 32 * i); n1[i] = *(const bf16x8*)(ap + (size_t)16 * lda + kn + 32 * i); nb[i] = *(const bf16x8*)(bp + kn + 32 * i); }
; #pragma unroll
;             for (int i = 0; i < 8; ++i) { acc0 = __builtin_amdgcn_mfma_f32_16x16x32_bf16(b[i], a0[i], acc0, 0, 0, 0); acc1 = __builtin_amdgcn_mfma_f32_16x16x32_bf16(b[i], a1[i], acc1, 0, 0, 0); }
; #pragma unroll
;             for (int i = 0; i < 8; ++i) { a0[i] = n0[i]; a1[i] = n1[i]; b[i] = nb[i]; }
;         }
;         *(LAS f32x4*)(Cs + fr * ldc + ct * 16 + 4 * fq) = acc0; *(LAS f32x4*)(Cs + (16 + fr) * ldc + ct * 16 + 4 * fq) = acc1;
;     }
;     __syncthreads();
	v_mfma_f32_16x16x32_bf16 v[16:19], v[168:171], v[92:95], v[16:19]
	v_mfma_f32_16x16x32_bf16 v[20:23], v[168:171], v[96:99], v[20:23]
	ds_read_b128 v[92:95], v4 offset:896
	ds_read_b128 v[96:99], v4 offset:33920
	s_waitcnt vmcnt(19) lgkmcnt(4)
	v_mfma_f32_16x16x32_bf16 v[16:19], v[172:175], v[76:79], v[16:19]
	v_mfma_f32_16x16x32_bf16 v[20:23], v[172:175], v[80:83], v[20:23]
	ds_read_b128 v[76:79], v4 offset:960
	ds_read_b128 v[80:83], v4 offset:33984
	s_waitcnt vmcnt(18) lgkmcnt(4)
	v_mfma_f32_16x16x32_bf16 v[16:19], v[176:179], v[84:87], v[16:19]
	v_mfma_f32_16x16x32_bf16 v[20:23], v[176:179], v[88:91], v[20:23]
	ds_read_b128 v[84:87], v4 offset:1024
	ds_read_b128 v[88:91], v4 offset:34048
	s_waitcnt vmcnt(17) lgkmcnt(4)
	v_mfma_f32_16x16x32_bf16 v[16:19], v[180:183], v[92:95], v[16:19]
	v_mfma_f32_16x16x32_bf16 v[20:23], v[180:183], v[96:99], v[20:23]
	ds_read_b128 v[92:95], v4 offset:1088
	ds_read_b128 v[96:99], v4 offset:34112
	s_waitcnt vmcnt(16) lgkmcnt(4)
	v_mfma_f32_16x16x32_bf16 v[16:19], v[184:187], v[76:79], v[16:19]
	v_mfma_f32_16x16x32_bf16 v[20:23], v[184:187], v[80:83], v[20:23]
	ds_read_b128 v[76:79], v4 offset:1152
	ds_read_b128 v[80:83], v4 offset:34176
	s_waitcnt vmcnt(15) lgkmcnt(4)
	v_mfma_f32_16x16x32_bf16 v[16:19], v[188:191], v[84:87], v[16:19]
	v_mfma_f32_16x16x32_bf16 v[20:23], v[188:191], v[88:91], v[20:23]
	ds_read_b128 v[84:87], v4 offset:1216
	ds_read_b128 v[88:91], v4 offset:34240
	s_waitcnt vmcnt(14) lgkmcnt(4)
	v_mfma_f32_16x16x32_bf16 v[16:19], v[192:195], v[92:95], v[16:19]
	v_mfma_f32_16x16x32_bf16 v[20:23], v[192:195], v[96:99], v[20:23]
	ds_read_b128 v[92:95], v4 offset:1280
	ds_read_b128 v[96:99], v4 offset:34304
	s_waitcnt vmcnt(13) lgkmcnt(4)
	v_mfma_f32_16x16x32_bf16 v[16:19], v[196:199], v[76:79], v[16:19]
	v_mfma_f32_16x16x32_bf16 v[20:23], v[196:199], v[80:83], v[20:23]
	ds_read_b128 v[76:79], v4 offset:1344
	ds_read_b128 v[80:83], v4 offset:34368
	s_waitcnt vmcnt(12) lgkmcnt(4)
	v_mfma_f32_16x16x32_bf16 v[16:19], v[212:215], v[84:87], v[16:19]
	v_mfma_f32_16x16x32_bf16 v[20:23], v[212:215], v[88:91], v[20:23]
	ds_read_b128 v[84:87], v4 offset:1408
	ds_read_b128 v[88:91], v4 offset:34432
	s_waitcnt vmcnt(11) lgkmcnt(4)
	v_mfma_f32_16x16x32_bf16 v[16:19], v[216:219], v[92:95], v[16:19]
	v_mfma_f32_16x16x32_bf16 v[20:23], v[216:219], v[96:99], v[20:23]
	ds_read_b128 v[92:95], v4 offset:1472
	ds_read_b128 v[96:99], v4 offset:34496
	s_waitcnt vmcnt(10) lgkmcnt(4)
	v_mfma_f32_16x16x32_bf16 v[16:19], v[220:223], v[76:79], v[16:19]
	v_mfma_f32_16x16x32_bf16 v[20:23], v[220:223], v[80:83], v[20:23]
	ds_read_b128 v[76:79], v4 offset:1536
	ds_read_b128 v[80:83], v4 offset:34560
	s_waitcnt vmcnt(9) lgkmcnt(4)
	v_mfma_f32_16x16x32_bf16 v[16:19], v[224:227], v[84:87], v[16:19]
	v_mfma_f32_16x16x32_bf16 v[20:23], v[224:227], v[88:91], v[20:23]
	ds_read_b128 v[84:87], v4 offset:1600
	ds_read_b128 v[88:91], v4 offset:34624
	s_waitcnt vmcnt(8) lgkmcnt(4)
	v_mfma_f32_16x16x32_bf16 v[16:19], v[228:231], v[92:95], v[16:19]
	v_mfma_f32_16x16x32_bf16 v[20:23], v[228:231], v[96:99], v[20:23]
	ds_read_b128 v[92:95], v4 offset:1664
	ds_read_b128 v[96:99], v4 offset:34688
	s_waitcnt vmcnt(7) lgkmcnt(4)
	v_mfma_f32_16x16x32_bf16 v[16:19], v[124:127], v[76:79], v[16:19]
	v_mfma_f32_16x16x32_bf16 v[20:23], v[124:127], v[80:83], v[20:23]
	ds_read_b128 v[76:79], v4 offset:1728
	ds_read_b128 v[80:83], v4 offset:34752
	s_waitcnt vmcnt(6) lgkmcnt(4)
	v_mfma_f32_16x16x32_bf16 v[16:19], v[128:131], v[84:87], v[16:19]
	v_mfma_f32_16x16x32_bf16 v[20:23], v[128:131], v[88:91], v[20:23]
	ds_read_b128 v[84:87], v4 offset:1792
	ds_read_b128 v[88:91], v4 offset:34816
	s_waitcnt vmcnt(5) lgkmcnt(4)
	v_mfma_f32_16x16x32_bf16 v[16:19], v[132:135], v[92:95], v[16:19]
	v_mfma_f32_16x16x32_bf16 v[20:23], v[132:135], v[96:99], v[20:23]
	ds_read_b128 v[92:95], v4 offset:1856
	ds_read_b128 v[96:99], v4 offset:34880
	s_waitcnt vmcnt(4) lgkmcnt(4)
	v_mfma_f32_16x16x32_bf16 v[16:19], v[136:139], v[76:79], v[16:19]
	v_mfma_f32_16x16x32_bf16 v[20:23], v[136:139], v[80:83], v[20:23]
	ds_read_b128 v[76:79], v4 offset:1920
	ds_read_b128 v[80:83], v4 offset:34944
	s_waitcnt vmcnt(3) lgkmcnt(4)
	v_mfma_f32_16x16x32_bf16 v[16:19], v[140:143], v[84:87], v[16:19]
	v_mfma_f32_16x16x32_bf16 v[20:23], v[140:143], v[88:91], v[20:23]
	ds_read_b128 v[84:87], v4 offset:1984
	ds_read_b128 v[88:91], v4 offset:35008
	s_waitcnt vmcnt(2) lgkmcnt(4)
	v_mfma_f32_16x16x32_bf16 v[16:19], v[144:147], v[92:95], v[16:19]
	v_mfma_f32_16x16x32_bf16 v[20:23], v[144:147], v[96:99], v[20:23]
	s_waitcnt vmcnt(1) lgkmcnt(2)
	v_mfma_f32_16x16x32_bf16 v[16:19], v[148:151], v[76:79], v[16:19]
	v_mfma_f32_16x16x32_bf16 v[20:23], v[148:151], v[80:83], v[20:23]
	s_waitcnt vmcnt(0) lgkmcnt(0)
	v_mfma_f32_16x16x32_bf16 v[16:19], v[152:155], v[84:87], v[16:19]
	v_mfma_f32_16x16x32_bf16 v[20:23], v[152:155], v[88:91], v[20:23]
	s_nop 7
	s_nop 3
	s_lshl_b32 s20, s4, 6
	v_add_u32_e32 v6, s20, v5
	ds_write_b128 v6, v[16:19]
	ds_write_b128 v6, v[20:23] offset:12544
.Lmy_sk2_done:
	s_mov_b64 s[0:1], -1
